# SGU unit: all sixteen statistics loads of a thread issued before the first wait
# speedup vs baseline: 1.0075x; 1.0002x over previous
.LBB0_778:
	s_lshr_b32 s0, s10, 2
	s_and_b32 s0, s0, 0x1fffff8
	s_and_b32 s1, s10, 7
	s_or_b32 s4, s0, s1
	s_mov_b64 s[0:1], s[86:87]
	v_mbcnt_lo_u32_b32 v51, -1, 0
	v_mbcnt_hi_u32_b32 v51, -1, v51
	s_add_u32 s2, s0, 0x9e84100
	v_add_u32_e32 v52, s75, v51
	s_addc_u32 s3, s1, 0
	s_lshl_b32 s12, s4, 7
	v_ashrrev_i32_e32 v53, 4, v52
	v_add_u32_e32 v18, s12, v53
	v_ashrrev_i32_e32 v19, 31, v18
	v_and_b32_e32 v50, 15, v51
	v_lshlrev_b64 v[2:3], 12, v[18:19]
	v_lshl_add_u64 v[2:3], s[2:3], 0, v[2:3]
	v_lshlrev_b32_e32 v0, 4, v50
	s_mov_b32 s7, 0x3727c5ac
	v_lshl_add_u64 v[14:15], v[2:3], 0, v[0:1]
	global_load_dwordx4 v[2:5], v[14:15], off offset:3072
	global_load_dwordx4 v[6:9], v[14:15], off offset:3328
	global_load_dwordx4 v[10:13], v[14:15], off offset:3584
	s_nop 0
	global_load_dwordx4 v[14:17], v[14:15], off offset:3840
	v_lshlrev_b32_e32 v19, 2, v51
	v_bitop3_b32 v57, v19, 4, v220 bitop3:0x6c
	v_add_u32_e32 v20, 32, v18
	v_add_u32_e32 v22, 64, v18
	v_add_u32_e32 v18, 0x60, v18
	v_bitop3_b32 v56, v19, 8, v220 bitop3:0x6c
	v_bitop3_b32 v55, v19, 16, v220 bitop3:0x6c
	v_bitop3_b32 v54, v19, 32, v220 bitop3:0x6c
	v_ashrrev_i32_e32 v21, 31, v20
	v_ashrrev_i32_e32 v23, 31, v22
	v_ashrrev_i32_e32 v19, 31, v18
	v_lshlrev_b64 v[20:21], 12, v[20:21]
	v_lshlrev_b64 v[22:23], 12, v[22:23]
	v_lshlrev_b64 v[18:19], 12, v[18:19]
	v_lshl_add_u64 v[20:21], s[2:3], 0, v[20:21]
	v_lshl_add_u64 v[22:23], s[2:3], 0, v[22:23]
	v_readlane_b32 s4, v254, 18
	v_cmp_eq_u32_e32 vcc, 0, v50
	v_lshl_add_u64 v[92:93], v[20:21], 0, v[0:1]
	v_lshl_add_u64 v[94:95], v[22:23], 0, v[0:1]
	v_lshl_add_u64 v[96:97], s[2:3], 0, v[18:19]
	v_lshl_add_u64 v[96:97], v[96:97], 0, v[0:1]
	global_load_dwordx4 v[46:49], v[92:93], off offset:3072
	global_load_dwordx4 v[42:45], v[92:93], off offset:3328
	global_load_dwordx4 v[38:41], v[92:93], off offset:3584
	global_load_dwordx4 v[34:37], v[92:93], off offset:3840
	global_load_dwordx4 v[30:33], v[94:95], off offset:3072
	global_load_dwordx4 v[26:29], v[94:95], off offset:3328
	global_load_dwordx4 v[22:25], v[94:95], off offset:3584
	global_load_dwordx4 v[18:21], v[94:95], off offset:3840
	global_load_dwordx4 v[100:103], v[96:97], off offset:3072
	global_load_dwordx4 v[104:107], v[96:97], off offset:3328
	global_load_dwordx4 v[108:111], v[96:97], off offset:3584
	global_load_dwordx4 v[112:115], v[96:97], off offset:3840
	s_waitcnt vmcnt(12)
	v_lshlrev_b32_e32 v59, 16, v2
	v_and_b32_e32 v60, 0xffff0000, v2
	v_lshlrev_b32_e32 v61, 16, v3
	v_and_b32_e32 v62, 0xffff0000, v3
	v_add_f32_e32 v2, v59, v60
	v_lshlrev_b32_e32 v63, 16, v4
	v_and_b32_e32 v64, 0xffff0000, v4
	v_add_f32_e32 v3, v61, v62
	v_add_f32_e32 v2, 0, v2
	v_lshlrev_b32_e32 v65, 16, v5
	v_and_b32_e32 v66, 0xffff0000, v5
	v_add_f32_e32 v4, v63, v64
	v_add_f32_e32 v2, v3, v2
	v_lshlrev_b32_e32 v67, 16, v6
	v_and_b32_e32 v68, 0xffff0000, v6
	v_add_f32_e32 v5, v65, v66
	v_add_f32_e32 v2, v4, v2
	v_lshlrev_b32_e32 v69, 16, v7
	v_and_b32_e32 v70, 0xffff0000, v7
	v_add_f32_e32 v6, v67, v68
	v_add_f32_e32 v2, v5, v2
	v_lshlrev_b32_e32 v71, 16, v8
	v_and_b32_e32 v72, 0xffff0000, v8
	v_add_f32_e32 v7, v69, v70
	v_add_f32_e32 v2, v6, v2
	v_lshlrev_b32_e32 v73, 16, v9
	v_and_b32_e32 v74, 0xffff0000, v9
	v_add_f32_e32 v8, v71, v72
	v_add_f32_e32 v2, v7, v2
	v_lshlrev_b32_e32 v75, 16, v10
	v_and_b32_e32 v76, 0xffff0000, v10
	v_add_f32_e32 v9, v73, v74
	v_add_f32_e32 v2, v8, v2
	v_lshlrev_b32_e32 v77, 16, v11
	v_and_b32_e32 v78, 0xffff0000, v11
	v_add_f32_e32 v10, v75, v76
	v_add_f32_e32 v2, v9, v2
	v_lshlrev_b32_e32 v79, 16, v12
	v_and_b32_e32 v80, 0xffff0000, v12
	v_add_f32_e32 v11, v77, v78
	v_add_f32_e32 v2, v10, v2
	v_lshlrev_b32_e32 v81, 16, v13
	v_and_b32_e32 v82, 0xffff0000, v13
	v_add_f32_e32 v12, v79, v80
	v_add_f32_e32 v2, v11, v2
	v_lshlrev_b32_e32 v83, 16, v14
	v_and_b32_e32 v84, 0xffff0000, v14
	v_add_f32_e32 v13, v81, v82
	v_add_f32_e32 v2, v12, v2
	v_lshlrev_b32_e32 v85, 16, v15
	v_and_b32_e32 v86, 0xffff0000, v15
	v_add_f32_e32 v14, v83, v84
	v_add_f32_e32 v2, v13, v2
	v_lshlrev_b32_e32 v87, 16, v16
	v_and_b32_e32 v88, 0xffff0000, v16
	v_add_f32_e32 v15, v85, v86
	v_add_f32_e32 v2, v14, v2
	v_lshlrev_b32_e32 v89, 16, v17
	v_and_b32_e32 v90, 0xffff0000, v17
	v_add_f32_e32 v16, v87, v88
	v_add_f32_e32 v2, v15, v2
	v_add_f32_e32 v17, v89, v90
	v_add_f32_e32 v2, v16, v2
	v_add_f32_e32 v8, v17, v2
	s_nop 1
	v_mov_b32_dpp v9, v8 quad_perm:[1,0,3,2] row_mask:0xf bank_mask:0xf
	s_waitcnt lgkmcnt(0)
	v_add_f32_e32 v0, v8, v9
	s_nop 1
	v_mov_b32_dpp v8, v0 quad_perm:[2,3,0,1] row_mask:0xf bank_mask:0xf
	s_waitcnt lgkmcnt(0)
	v_add_f32_e32 v0, v0, v8
	s_nop 1
	v_mov_b32_dpp v4, v0 row_half_mirror row_mask:0xf bank_mask:0xf
	s_waitcnt lgkmcnt(0)
	v_add_f32_e32 v0, v0, v4
	s_nop 1
	v_mov_b32_dpp v58, v0 row_mirror row_mask:0xf bank_mask:0xf
	s_waitcnt lgkmcnt(0)
	v_add_f32_e32 v58, v0, v58
	v_fmac_f32_e32 v60, 0xbb000000, v58
	v_fmac_f32_e32 v59, 0xbb000000, v58
	v_fmac_f32_e32 v62, 0xbb000000, v58
	v_mul_f32_e32 v0, v60, v60
	v_fmac_f32_e32 v61, 0xbb000000, v58
	v_fmac_f32_e32 v0, v59, v59
	v_mul_f32_e32 v59, v62, v62
	v_fmac_f32_e32 v59, v61, v61
	v_fmac_f32_e32 v64, 0xbb000000, v58
	v_add_f32_e32 v0, v0, v59
	v_fmac_f32_e32 v63, 0xbb000000, v58
	v_mul_f32_e32 v59, v64, v64
	v_fmac_f32_e32 v59, v63, v63
	v_fmac_f32_e32 v66, 0xbb000000, v58
	v_add_f32_e32 v0, v59, v0
	v_fmac_f32_e32 v65, 0xbb000000, v58
	v_mul_f32_e32 v59, v66, v66
	v_fmac_f32_e32 v59, v65, v65
	v_fmac_f32_e32 v68, 0xbb000000, v58
	v_add_f32_e32 v0, v59, v0
	v_fmac_f32_e32 v67, 0xbb000000, v58
	v_mul_f32_e32 v59, v68, v68
	v_fmac_f32_e32 v59, v67, v67
	v_fmac_f32_e32 v70, 0xbb000000, v58
	v_add_f32_e32 v0, v59, v0
	v_fmac_f32_e32 v69, 0xbb000000, v58
	v_mul_f32_e32 v59, v70, v70
	v_fmac_f32_e32 v59, v69, v69
	v_fmac_f32_e32 v72, 0xbb000000, v58
	v_add_f32_e32 v0, v59, v0
	v_fmac_f32_e32 v71, 0xbb000000, v58
	v_mul_f32_e32 v59, v72, v72
	v_fmac_f32_e32 v59, v71, v71
	v_fmac_f32_e32 v74, 0xbb000000, v58
	v_add_f32_e32 v0, v59, v0
	v_fmac_f32_e32 v73, 0xbb000000, v58
	v_mul_f32_e32 v59, v74, v74
	v_fmac_f32_e32 v59, v73, v73
	v_fmac_f32_e32 v76, 0xbb000000, v58
	v_add_f32_e32 v0, v59, v0
	v_fmac_f32_e32 v75, 0xbb000000, v58
	v_mul_f32_e32 v59, v76, v76
	v_fmac_f32_e32 v59, v75, v75
	v_fmac_f32_e32 v78, 0xbb000000, v58
	v_add_f32_e32 v0, v59, v0
	v_fmac_f32_e32 v77, 0xbb000000, v58
	v_mul_f32_e32 v59, v78, v78
	v_fmac_f32_e32 v59, v77, v77
	v_fmac_f32_e32 v80, 0xbb000000, v58
	v_add_f32_e32 v0, v59, v0
	v_fmac_f32_e32 v79, 0xbb000000, v58
	v_mul_f32_e32 v59, v80, v80
	v_fmac_f32_e32 v59, v79, v79
	v_fmac_f32_e32 v82, 0xbb000000, v58
	v_add_f32_e32 v0, v59, v0
	v_fmac_f32_e32 v81, 0xbb000000, v58
	v_mul_f32_e32 v59, v82, v82
	v_fmac_f32_e32 v59, v81, v81
	v_fmac_f32_e32 v84, 0xbb000000, v58
	v_add_f32_e32 v0, v59, v0
	v_fmac_f32_e32 v83, 0xbb000000, v58
	v_mul_f32_e32 v59, v84, v84
	v_fmac_f32_e32 v59, v83, v83
	v_fmac_f32_e32 v86, 0xbb000000, v58
	v_add_f32_e32 v0, v59, v0
	v_fmac_f32_e32 v85, 0xbb000000, v58
	v_mul_f32_e32 v59, v86, v86
	v_fmac_f32_e32 v59, v85, v85
	v_fmac_f32_e32 v88, 0xbb000000, v58
	v_add_f32_e32 v0, v59, v0
	v_fmac_f32_e32 v87, 0xbb000000, v58
	v_mul_f32_e32 v59, v88, v88
	v_fmac_f32_e32 v59, v87, v87
	v_fmac_f32_e32 v90, 0xbb000000, v58
	v_add_f32_e32 v0, v59, v0
	v_fmac_f32_e32 v89, 0xbb000000, v58
	v_mul_f32_e32 v59, v90, v90
	v_fmac_f32_e32 v59, v89, v89
	v_add_f32_e32 v0, v59, v0
	s_nop 1
	v_mov_b32_dpp v59, v0 quad_perm:[1,0,3,2] row_mask:0xf bank_mask:0xf
	s_waitcnt lgkmcnt(0)
	v_add_f32_e32 v0, v0, v59
	s_nop 1
	v_mov_b32_dpp v59, v0 quad_perm:[2,3,0,1] row_mask:0xf bank_mask:0xf
	s_waitcnt lgkmcnt(0)
	v_add_f32_e32 v0, v0, v59
	s_nop 1
	v_mov_b32_dpp v59, v0 row_half_mirror row_mask:0xf bank_mask:0xf
	s_waitcnt lgkmcnt(0)
	v_add_f32_e32 v59, v0, v59
	s_nop 1
	v_mov_b32_dpp v60, v59 row_mirror row_mask:0xf bank_mask:0xf
	v_lshl_add_u32 v0, v53, 3, s4
	s_and_saveexec_b64 s[4:5], vcc
	s_cbranch_execz .LBB0_780
	s_waitcnt lgkmcnt(0)
	v_add_f32_e32 v59, v59, v60
	v_mov_b32_e32 v60, s7
	v_fmamk_f32 v59, v59, 0x3b000000, v60
	v_rsq_f32_e32 v59, v59
	v_mul_f32_e32 v58, 0x3b000000, v58
	ds_write_b64 v0, v[58:59]

.LBB0_784:
	s_or_b64 exec, exec, s[4:5]
	s_waitcnt vmcnt(0)
	v_mov_b64_e32 v[14:15], v[100:101]
	v_mov_b64_e32 v[16:17], v[102:103]
	v_mov_b64_e32 v[10:11], v[104:105]
	v_mov_b64_e32 v[12:13], v[106:107]
	v_mov_b64_e32 v[6:7], v[108:109]
	v_mov_b64_e32 v[8:9], v[110:111]
	v_mov_b64_e32 v[2:3], v[112:113]
	v_mov_b64_e32 v[4:5], v[114:115]
	s_waitcnt vmcnt(3)
	v_lshlrev_b32_e32 v18, 16, v14
	v_and_b32_e32 v14, 0xffff0000, v14
	v_add_f32_e32 v19, v18, v14
	s_waitcnt lgkmcnt(0)
	v_lshlrev_b32_e32 v20, 16, v15
	v_and_b32_e32 v15, 0xffff0000, v15
	v_add_f32_e32 v19, 0, v19
	v_add_f32_e32 v21, v20, v15
	v_add_f32_e32 v19, v21, v19
	v_lshlrev_b32_e32 v21, 16, v16
	v_and_b32_e32 v16, 0xffff0000, v16
	v_add_f32_e32 v22, v21, v16
	v_add_f32_e32 v19, v22, v19
	v_lshlrev_b32_e32 v22, 16, v17
	v_and_b32_e32 v17, 0xffff0000, v17
	v_add_f32_e32 v23, v22, v17
	v_add_f32_e32 v19, v23, v19
	s_waitcnt vmcnt(2)
	v_lshlrev_b32_e32 v23, 16, v10
	v_and_b32_e32 v10, 0xffff0000, v10
	v_add_f32_e32 v24, v23, v10
	v_add_f32_e32 v19, v24, v19
	v_lshlrev_b32_e32 v24, 16, v11
	v_and_b32_e32 v11, 0xffff0000, v11
	v_add_f32_e32 v25, v24, v11
	v_add_f32_e32 v19, v25, v19
	v_lshlrev_b32_e32 v25, 16, v12
	v_and_b32_e32 v12, 0xffff0000, v12
	v_add_f32_e32 v26, v25, v12
	v_add_f32_e32 v19, v26, v19
	v_lshlrev_b32_e32 v26, 16, v13
	v_and_b32_e32 v13, 0xffff0000, v13
	v_add_f32_e32 v27, v26, v13
	v_add_f32_e32 v19, v27, v19
	s_waitcnt vmcnt(1)
	v_lshlrev_b32_e32 v27, 16, v6
	v_and_b32_e32 v6, 0xffff0000, v6
	v_add_f32_e32 v28, v27, v6
	v_add_f32_e32 v19, v28, v19
	v_lshlrev_b32_e32 v28, 16, v7
	v_and_b32_e32 v7, 0xffff0000, v7
	v_add_f32_e32 v29, v28, v7
	v_add_f32_e32 v19, v29, v19
	v_lshlrev_b32_e32 v29, 16, v8
	v_and_b32_e32 v8, 0xffff0000, v8
	v_add_f32_e32 v30, v29, v8
	v_add_f32_e32 v19, v30, v19
	v_lshlrev_b32_e32 v30, 16, v9
	v_and_b32_e32 v9, 0xffff0000, v9
	v_add_f32_e32 v31, v30, v9
	v_add_f32_e32 v19, v31, v19
	s_waitcnt vmcnt(0)
	v_lshlrev_b32_e32 v31, 16, v2
	v_and_b32_e32 v32, 0xffff0000, v2
	v_add_f32_e32 v2, v31, v32
	v_add_f32_e32 v2, v2, v19
	v_lshlrev_b32_e32 v19, 16, v3
	v_and_b32_e32 v3, 0xffff0000, v3
	v_add_f32_e32 v33, v19, v3
	v_add_f32_e32 v2, v33, v2
	v_lshlrev_b32_e32 v33, 16, v4
	v_and_b32_e32 v4, 0xffff0000, v4
	v_add_f32_e32 v34, v33, v4
	v_add_f32_e32 v2, v34, v2
	v_lshlrev_b32_e32 v34, 16, v5
	v_and_b32_e32 v5, 0xffff0000, v5
	v_add_f32_e32 v35, v34, v5
	v_add_f32_e32 v2, v35, v2
	s_nop 1
	v_mov_b32_dpp v35, v2 quad_perm:[1,0,3,2] row_mask:0xf bank_mask:0xf
	s_waitcnt lgkmcnt(0)
	v_add_f32_e32 v2, v2, v35
	s_nop 1
	v_mov_b32_dpp v35, v2 quad_perm:[2,3,0,1] row_mask:0xf bank_mask:0xf
	s_waitcnt lgkmcnt(0)
	v_add_f32_e32 v2, v2, v35
	s_nop 1
	v_mov_b32_dpp v35, v2 row_half_mirror row_mask:0xf bank_mask:0xf
	s_waitcnt lgkmcnt(0)
	v_add_f32_e32 v2, v2, v35
	s_nop 1
	v_mov_b32_dpp v35, v2 row_mirror row_mask:0xf bank_mask:0xf
	s_waitcnt lgkmcnt(0)
	v_add_f32_e32 v2, v2, v35
	v_fmac_f32_e32 v14, 0xbb000000, v2
	v_fmac_f32_e32 v15, 0xbb000000, v2
	v_fmac_f32_e32 v18, 0xbb000000, v2
	v_mul_f32_e32 v14, v14, v14
	v_fmac_f32_e32 v20, 0xbb000000, v2
	v_mul_f32_e32 v15, v15, v15
	v_fmac_f32_e32 v14, v18, v18
	v_fmac_f32_e32 v15, v20, v20
	v_fmac_f32_e32 v16, 0xbb000000, v2
	v_add_f32_e32 v14, v14, v15
	v_fmac_f32_e32 v21, 0xbb000000, v2
	v_mul_f32_e32 v15, v16, v16
	v_fmac_f32_e32 v15, v21, v21
	v_fmac_f32_e32 v17, 0xbb000000, v2
	v_add_f32_e32 v14, v15, v14
	v_fmac_f32_e32 v22, 0xbb000000, v2
	v_mul_f32_e32 v15, v17, v17
	v_fmac_f32_e32 v10, 0xbb000000, v2
	v_fmac_f32_e32 v15, v22, v22
	v_fmac_f32_e32 v23, 0xbb000000, v2
	v_mul_f32_e32 v10, v10, v10
	v_fmac_f32_e32 v11, 0xbb000000, v2
	v_add_f32_e32 v14, v15, v14
	v_fmac_f32_e32 v10, v23, v23
	v_fmac_f32_e32 v24, 0xbb000000, v2
	v_mul_f32_e32 v11, v11, v11
	v_add_f32_e32 v10, v10, v14
	v_fmac_f32_e32 v11, v24, v24
	v_fmac_f32_e32 v12, 0xbb000000, v2
	v_add_f32_e32 v10, v11, v10
	v_fmac_f32_e32 v25, 0xbb000000, v2
	v_mul_f32_e32 v11, v12, v12
	v_fmac_f32_e32 v11, v25, v25
	v_fmac_f32_e32 v13, 0xbb000000, v2
	v_add_f32_e32 v10, v11, v10
	v_fmac_f32_e32 v26, 0xbb000000, v2
	v_mul_f32_e32 v11, v13, v13
	v_fmac_f32_e32 v6, 0xbb000000, v2
	v_fmac_f32_e32 v11, v26, v26
	v_fmac_f32_e32 v27, 0xbb000000, v2
	v_mul_f32_e32 v6, v6, v6
	v_fmac_f32_e32 v7, 0xbb000000, v2
	v_add_f32_e32 v10, v11, v10
	v_fmac_f32_e32 v6, v27, v27
	v_fmac_f32_e32 v28, 0xbb000000, v2
	v_mul_f32_e32 v7, v7, v7
	v_add_f32_e32 v6, v6, v10
	v_fmac_f32_e32 v7, v28, v28
	v_fmac_f32_e32 v8, 0xbb000000, v2
	v_add_f32_e32 v6, v7, v6
	v_fmac_f32_e32 v29, 0xbb000000, v2
	v_mul_f32_e32 v7, v8, v8
	v_fmac_f32_e32 v7, v29, v29
	v_fmac_f32_e32 v9, 0xbb000000, v2
	v_add_f32_e32 v6, v7, v6
	v_fmac_f32_e32 v30, 0xbb000000, v2
	v_mul_f32_e32 v7, v9, v9
	v_fmac_f32_e32 v7, v30, v30
	v_fmac_f32_e32 v32, 0xbb000000, v2
	v_add_f32_e32 v6, v7, v6
	v_fmac_f32_e32 v31, 0xbb000000, v2
	v_mul_f32_e32 v7, v32, v32
	v_fmac_f32_e32 v3, 0xbb000000, v2
	v_fmac_f32_e32 v7, v31, v31
	v_fmac_f32_e32 v19, 0xbb000000, v2
	v_mul_f32_e32 v3, v3, v3
	v_fmac_f32_e32 v4, 0xbb000000, v2
	v_add_f32_e32 v6, v7, v6
	v_fmac_f32_e32 v3, v19, v19
	v_fmac_f32_e32 v33, 0xbb000000, v2
	v_mul_f32_e32 v4, v4, v4
	v_add_f32_e32 v3, v3, v6
	v_fmac_f32_e32 v4, v33, v33
	v_fmac_f32_e32 v5, 0xbb000000, v2
	v_add_f32_e32 v3, v4, v3
	v_fmac_f32_e32 v34, 0xbb000000, v2
	v_mul_f32_e32 v4, v5, v5
	v_fmac_f32_e32 v4, v34, v34
	v_add_f32_e32 v3, v4, v3
	s_nop 1
	v_mov_b32_dpp v4, v3 quad_perm:[1,0,3,2] row_mask:0xf bank_mask:0xf
	s_waitcnt lgkmcnt(0)
	v_add_f32_e32 v3, v3, v4
	s_nop 1
	v_mov_b32_dpp v4, v3 quad_perm:[2,3,0,1] row_mask:0xf bank_mask:0xf
	s_waitcnt lgkmcnt(0)
	v_add_f32_e32 v3, v3, v4
	s_nop 1
	v_mov_b32_dpp v4, v3 row_half_mirror row_mask:0xf bank_mask:0xf
	s_waitcnt lgkmcnt(0)
	v_add_f32_e32 v3, v3, v4
	s_nop 1
	v_mov_b32_dpp v4, v3 row_mirror row_mask:0xf bank_mask:0xf
	s_and_saveexec_b64 s[4:5], vcc
	s_cbranch_execz .LBB0_786
	s_waitcnt lgkmcnt(0)
	v_add_f32_e32 v3, v3, v4
	v_mov_b32_e32 v4, s7
	v_fmac_f32_e32 v4, 0x3b000000, v3
	v_rsq_f32_e32 v3, v4
	v_mul_f32_e32 v2, 0x3b000000, v2
	ds_write_b64 v0, v[2:3] offset:768
